# prep_wprime rewritten: wave = 64 n' x 4 k tile, CW fragment resident in VGPRs, fn_w_in rows broadcast-loaded, f32 FMA (was per-lane strided rows + 160 loads per output)
# speedup vs baseline: 1.0332x; 1.0074x over previous
; DI int tid_opaque() { int t = threadIdx.x; asm volatile("" : "+v"(t)); return t; }
; DI u16 f2bf(float x) { return (u16)(pack2(x, 0.f) & 0xffffu); }
; DI void prep_wprime(const Params& p) {
;   const long gt = (long)blockIdx.x * NTHR + tid_opaque(), gn = (long)gridDim.x * NTHR;
;   for (long id = gt; id < 2048L * 1024; id += gn) {
;     const int k = (int)(id & 1023), np = (int)(id >> 10), g = np >> 8, col = np & 255;
;     const float4* wi = (const float4*)(p.fn_w_in + (long)k * 2048 + g * 128);
;     const float* cw = p.CW + (long)g * 128 * 256 + col;
;     float a = 0.f;
;     for (int c4 = 0; c4 < 32; ++c4) {
;       float4 v = wi[c4];
;       a += v.x * cw[(c4 * 4 + 0) * 256] + v.y * cw[(c4 * 4 + 1) * 256] + v.z * cw[(c4 * 4 + 2) * 256] + v.w * cw[(c4 * 4 + 3) * 256];
;     }
;     p.Wfn[id] = f2bf(a * p.norm_g[k]);
;   }
; }
.LBB0_62:
	s_or_b64 exec, exec, s[6:7]
	v_mov_b32_e32 v2, v182
	s_barrier
	s_mov_b64 s[6:7], exec
	s_load_dwordx2 s[22:23], s[0:1], 0x20
	s_load_dwordx2 s[16:17], s[0:1], 0x28
	s_load_dwordx2 s[18:19], s[0:1], 0xe8
	s_load_dwordx2 s[20:21], s[0:1], 0x78
	v_lshrrev_b32_e32 v56, 6, v182
	v_and_b32_e32 v64, 63, v182
	s_nop 0
	v_readfirstlane_b32 s8, v56
	s_nop 3
	s_lshl_b32 s9, s82, 3
	s_add_i32 s8, s8, s9
	s_lshl_b32 s9, s42, 3
	s_mov_b32 s12, -1
	s_mov_b64 s[24:25], 0x1000
	s_waitcnt lgkmcnt(0)
	s_cmp_lt_u32 s8, 0x2000
	s_cbranch_scc0 .Lwp_done
.Lwp_tile:
	s_and_b32 s10, s8, 31
	s_lshr_b32 s11, s8, 5
	s_cmp_eq_u32 s10, s12
	s_cbranch_scc1 .Lwp_havecw
	s_mov_b32 s12, s10
	s_lshr_b32 s14, s10, 2
	s_lshl_b32 s14, s14, 17
	s_and_b32 s15, s10, 3
	s_lshl_b32 s15, s15, 8
	s_add_i32 s14, s14, s15
	v_lshl_add_u32 v38, v64, 2, s14
	v_mov_b32_e32 v37, s19
	v_add_co_u32_e32 v36, vcc, s18, v38
	s_nop 1
	v_addc_co_u32_e32 v37, vcc, 0, v37, vcc
	global_load_dword v84, v[36:37], off
	global_load_dword v85, v[36:37], off offset:1024
	global_load_dword v86, v[36:37], off offset:2048
	global_load_dword v87, v[36:37], off offset:3072
	v_lshl_add_u64 v[36:37], v[36:37], 0, s[24:25]
	global_load_dword v88, v[36:37], off
	global_load_dword v89, v[36:37], off offset:1024
	global_load_dword v90, v[36:37], off offset:2048
	global_load_dword v91, v[36:37], off offset:3072
	v_lshl_add_u64 v[36:37], v[36:37], 0, s[24:25]
	global_load_dword v92, v[36:37], off
	global_load_dword v93, v[36:37], off offset:1024
	global_load_dword v94, v[36:37], off offset:2048
	global_load_dword v95, v[36:37], off offset:3072
	v_lshl_add_u64 v[36:37], v[36:37], 0, s[24:25]
	global_load_dword v96, v[36:37], off
	global_load_dword v97, v[36:37], off offset:1024
	global_load_dword v98, v[36:37], off offset:2048
	global_load_dword v99, v[36:37], off offset:3072
	v_lshl_add_u64 v[36:37], v[36:37], 0, s[24:25]
	global_load_dword v100, v[36:37], off
	global_load_dword v101, v[36:37], off offset:1024
	global_load_dword v102, v[36:37], off offset:2048
	global_load_dword v103, v[36:37], off offset:3072
	v_lshl_add_u64 v[36:37], v[36:37], 0, s[24:25]
	global_load_dword v104, v[36:37], off
	global_load_dword v105, v[36:37], off offset:1024
	global_load_dword v106, v[36:37], off offset:2048
	global_load_dword v107, v[36:37], off offset:3072
	v_lshl_add_u64 v[36:37], v[36:37], 0, s[24:25]
	global_load_dword v108, v[36:37], off
	global_load_dword v109, v[36:37], off offset:1024
	global_load_dword v110, v[36:37], off offset:2048
	global_load_dword v111, v[36:37], off offset:3072
	v_lshl_add_u64 v[36:37], v[36:37], 0, s[24:25]
	global_load_dword v112, v[36:37], off
	global_load_dword v113, v[36:37], off offset:1024
	global_load_dword v114, v[36:37], off offset:2048
	global_load_dword v115, v[36:37], off offset:3072
	v_lshl_add_u64 v[36:37], v[36:37], 0, s[24:25]
	global_load_dword v116, v[36:37], off
	global_load_dword v117, v[36:37], off offset:1024
	global_load_dword v118, v[36:37], off offset:2048
	global_load_dword v119, v[36:37], off offset:3072
	v_lshl_add_u64 v[36:37], v[36:37], 0, s[24:25]
	global_load_dword v120, v[36:37], off
	global_load_dword v121, v[36:37], off offset:1024
	global_load_dword v122, v[36:37], off offset:2048
	global_load_dword v123, v[36:37], off offset:3072
	v_lshl_add_u64 v[36:37], v[36:37], 0, s[24:25]
	global_load_dword v124, v[36:37], off
	global_load_dword v125, v[36:37], off offset:1024
	global_load_dword v126, v[36:37], off offset:2048
	global_load_dword v127, v[36:37], off offset:3072
	v_lshl_add_u64 v[36:37], v[36:37], 0, s[24:25]
	global_load_dword v128, v[36:37], off
	global_load_dword v129, v[36:37], off offset:1024
	global_load_dword v130, v[36:37], off offset:2048
	global_load_dword v131, v[36:37], off offset:3072
	v_lshl_add_u64 v[36:37], v[36:37], 0, s[24:25]
	global_load_dword v132, v[36:37], off
	global_load_dword v133, v[36:37], off offset:1024
	global_load_dword v134, v[36:37], off offset:2048
	global_load_dword v135, v[36:37], off offset:3072
	v_lshl_add_u64 v[36:37], v[36:37], 0, s[24:25]
	global_load_dword v136, v[36:37], off
	global_load_dword v137, v[36:37], off offset:1024
	global_load_dword v138, v[36:37], off offset:2048
	global_load_dword v139, v[36:37], off offset:3072
	v_lshl_add_u64 v[36:37], v[36:37], 0, s[24:25]
	global_load_dword v140, v[36:37], off
	global_load_dword v141, v[36:37], off offset:1024
	global_load_dword v142, v[36:37], off offset:2048
	global_load_dword v143, v[36:37], off offset:3072
	v_lshl_add_u64 v[36:37], v[36:37], 0, s[24:25]
	global_load_dword v144, v[36:37], off
	global_load_dword v145, v[36:37], off offset:1024
	global_load_dword v146, v[36:37], off offset:2048
	global_load_dword v147, v[36:37], off offset:3072
	v_lshl_add_u64 v[36:37], v[36:37], 0, s[24:25]
	global_load_dword v148, v[36:37], off
	global_load_dword v149, v[36:37], off offset:1024
	global_load_dword v150, v[36:37], off offset:2048
	global_load_dword v151, v[36:37], off offset:3072
	v_lshl_add_u64 v[36:37], v[36:37], 0, s[24:25]
	global_load_dword v152, v[36:37], off
	global_load_dword v153, v[36:37], off offset:1024
	global_load_dword v154, v[36:37], off offset:2048
	global_load_dword v155, v[36:37], off offset:3072
	v_lshl_add_u64 v[36:37], v[36:37], 0, s[24:25]
	global_load_dword v156, v[36:37], off
	global_load_dword v157, v[36:37], off offset:1024
	global_load_dword v158, v[36:37], off offset:2048
	global_load_dword v159, v[36:37], off offset:3072
	v_lshl_add_u64 v[36:37], v[36:37], 0, s[24:25]
	global_load_dword v160, v[36:37], off
	global_load_dword v161, v[36:37], off offset:1024
	global_load_dword v162, v[36:37], off offset:2048
; DI int tid_opaque() { int t = threadIdx.x; asm volatile("" : "+v"(t)); return t; }
; DI void prep_wprime(const Params& p) {
;   const long gt = (long)blockIdx.x * NTHR + tid_opaque(), gn = (long)gridDim.x * NTHR;
;   for (long id = gt; id < 2048L * 1024; id += gn) {
;     const int k = (int)(id & 1023), np = (int)(id >> 10), g = np >> 8, col = np & 255;
;     const float4* wi = (const float4*)(p.fn_w_in + (long)k * 2048 + g * 128);
;     const float* cw = p.CW + (long)g * 128 * 256 + col;
;     float a = 0.f;
;     for (int c4 = 0; c4 < 32; ++c4) {
;       float4 v = wi[c4];
;       a += v.x * cw[(c4 * 4 + 0) * 256] + v.y * cw[(c4 * 4 + 1) * 256] + v.z * cw[(c4 * 4 + 2) * 256] + v.w * cw[(c4 * 4 + 3) * 256];
;     }
	global_load_dword v163, v[36:37], off offset:3072
	v_lshl_add_u64 v[36:37], v[36:37], 0, s[24:25]
	global_load_dword v164, v[36:37], off
	global_load_dword v165, v[36:37], off offset:1024
	global_load_dword v166, v[36:37], off offset:2048
	global_load_dword v167, v[36:37], off offset:3072
	v_lshl_add_u64 v[36:37], v[36:37], 0, s[24:25]
	global_load_dword v168, v[36:37], off
	global_load_dword v169, v[36:37], off offset:1024
	global_load_dword v170, v[36:37], off offset:2048
	global_load_dword v171, v[36:37], off offset:3072
	v_lshl_add_u64 v[36:37], v[36:37], 0, s[24:25]
	global_load_dword v172, v[36:37], off
	global_load_dword v173, v[36:37], off offset:1024
	global_load_dword v174, v[36:37], off offset:2048
	global_load_dword v175, v[36:37], off offset:3072
	v_lshl_add_u64 v[36:37], v[36:37], 0, s[24:25]
	global_load_dword v176, v[36:37], off
	global_load_dword v177, v[36:37], off offset:1024
	global_load_dword v178, v[36:37], off offset:2048
	global_load_dword v179, v[36:37], off offset:3072
	v_lshl_add_u64 v[36:37], v[36:37], 0, s[24:25]
	global_load_dword v184, v[36:37], off
	global_load_dword v185, v[36:37], off offset:1024
	global_load_dword v186, v[36:37], off offset:2048
	global_load_dword v187, v[36:37], off offset:3072
	v_lshl_add_u64 v[36:37], v[36:37], 0, s[24:25]
	global_load_dword v188, v[36:37], off
	global_load_dword v189, v[36:37], off offset:1024
	global_load_dword v190, v[36:37], off offset:2048
	global_load_dword v191, v[36:37], off offset:3072
	v_lshl_add_u64 v[36:37], v[36:37], 0, s[24:25]
	global_load_dword v192, v[36:37], off
	global_load_dword v193, v[36:37], off offset:1024
	global_load_dword v194, v[36:37], off offset:2048
	global_load_dword v195, v[36:37], off offset:3072
	v_lshl_add_u64 v[36:37], v[36:37], 0, s[24:25]
	global_load_dword v196, v[36:37], off
	global_load_dword v197, v[36:37], off offset:1024
	global_load_dword v198, v[36:37], off offset:2048
	global_load_dword v199, v[36:37], off offset:3072
	v_lshl_add_u64 v[36:37], v[36:37], 0, s[24:25]
	global_load_dword v200, v[36:37], off
	global_load_dword v201, v[36:37], off offset:1024
	global_load_dword v202, v[36:37], off offset:2048
	global_load_dword v203, v[36:37], off offset:3072
	v_lshl_add_u64 v[36:37], v[36:37], 0, s[24:25]
	global_load_dword v204, v[36:37], off
	global_load_dword v205, v[36:37], off offset:1024
	global_load_dword v206, v[36:37], off offset:2048
	global_load_dword v207, v[36:37], off offset:3072
	v_lshl_add_u64 v[36:37], v[36:37], 0, s[24:25]
	global_load_dword v208, v[36:37], off
	global_load_dword v209, v[36:37], off offset:1024
	global_load_dword v210, v[36:37], off offset:2048
	global_load_dword v211, v[36:37], off offset:3072
	v_lshl_add_u64 v[36:37], v[36:37], 0, s[24:25]
	global_load_dword v212, v[36:37], off
	global_load_dword v213, v[36:37], off offset:1024
	global_load_dword v214, v[36:37], off offset:2048
	global_load_dword v215, v[36:37], off offset:3072
.Lwp_havecw:
	s_lshl_b32 s14, s11, 15
	s_lshr_b32 s15, s10, 2
	s_lshl_b32 s15, s15, 9
	s_add_u32 s26, s16, s14
	s_addc_u32 s27, s17, 0
	s_add_u32 s26, s26, s15
	s_addc_u32 s27, s27, 0
	v_mov_b32_e32 v40, s26
	v_mov_b32_e32 v41, s27
	s_add_u32 s28, s26, 0x2000
	s_addc_u32 s29, s27, 0
	v_mov_b32_e32 v42, s28
	v_mov_b32_e32 v43, s29
	s_add_u32 s28, s26, 0x4000
	s_addc_u32 s29, s27, 0
	v_mov_b32_e32 v44, s28
	v_mov_b32_e32 v45, s29
	s_add_u32 s28, s26, 0x6000
	s_addc_u32 s29, s27, 0
	v_mov_b32_e32 v46, s28
	v_mov_b32_e32 v47, s29
	s_lshl_b32 s14, s11, 4
	s_add_u32 s28, s22, s14
	s_addc_u32 s29, s23, 0
	v_mov_b32_e32 v50, s28
	v_mov_b32_e32 v51, s29
	global_load_dwordx4 v[52:55], v[50:51], off
	s_lshl_b32 s14, s10, 17
	s_lshl_b32 s15, s11, 3
	s_add_i32 s14, s14, s15
	v_lshl_add_u32 v38, v64, 11, s14
	v_mov_b32_e32 v49, s21
	v_add_co_u32_e32 v48, vcc, s20, v38
	s_nop 1
	v_addc_co_u32_e32 v49, vcc, 0, v49, vcc
	v_mov_b32_e32 v248, 0
	v_mov_b32_e32 v249, 0
	v_mov_b32_e32 v250, 0
	v_mov_b32_e32 v251, 0
	global_load_dwordx4 v[216:219], v[40:41], off
	global_load_dwordx4 v[220:223], v[40:41], off offset:16
	global_load_dwordx4 v[224:227], v[42:43], off
	global_load_dwordx4 v[228:231], v[42:43], off offset:16
	global_load_dwordx4 v[232:235], v[44:45], off
	global_load_dwordx4 v[236:239], v[44:45], off offset:16
	global_load_dwordx4 v[240:243], v[46:47], off
	global_load_dwordx4 v[244:247], v[46:47], off offset:16
	global_load_dwordx4 v[4:7], v[40:41], off offset:32
	global_load_dwordx4 v[8:11], v[40:41], off offset:48
	global_load_dwordx4 v[12:15], v[42:43], off offset:32
	global_load_dwordx4 v[16:19], v[42:43], off offset:48
	global_load_dwordx4 v[20:23], v[44:45], off offset:32
	global_load_dwordx4 v[24:27], v[44:45], off offset:48
	global_load_dwordx4 v[28:31], v[46:47], off offset:32
	global_load_dwordx4 v[32:35], v[46:47], off offset:48
	s_waitcnt vmcnt(8)
	v_fmac_f32_e32 v248, v216, v84
	v_fmac_f32_e32 v249, v224, v84
	v_fmac_f32_e32 v250, v232, v84
	v_fmac_f32_e32 v251, v240, v84
	v_fmac_f32_e32 v248, v217, v85
	v_fmac_f32_e32 v249, v225, v85
	v_fmac_f32_e32 v250, v233, v85
	v_fmac_f32_e32 v251, v241, v85
	v_fmac_f32_e32 v248, v218, v86
	v_fmac_f32_e32 v249, v226, v86
	v_fmac_f32_e32 v250, v234, v86
	v_fmac_f32_e32 v251, v242, v86
	v_fmac_f32_e32 v248, v219, v87
	v_fmac_f32_e32 v249, v227, v87
	v_fmac_f32_e32 v250, v235, v87
	v_fmac_f32_e32 v251, v243, v87
	v_fmac_f32_e32 v248, v220, v88
	v_fmac_f32_e32 v249, v228, v88
	v_fmac_f32_e32 v250, v236, v88
	v_fmac_f32_e32 v251, v244, v88
	v_fmac_f32_e32 v248, v221, v89
	v_fmac_f32_e32 v249, v229, v89
	v_fmac_f32_e32 v250, v237, v89
	v_fmac_f32_e32 v251, v245, v89
	v_fmac_f32_e32 v248, v222, v90
	v_fmac_f32_e32 v249, v230, v90
	v_fmac_f32_e32 v250, v238, v90
	v_fmac_f32_e32 v251, v246, v90
	v_fmac_f32_e32 v248, v223, v91
	v_fmac_f32_e32 v249, v231, v91
	v_fmac_f32_e32 v250, v239, v91
	v_fmac_f32_e32 v251, v247, v91
	global_load_dwordx4 v[216:219], v[40:41], off offset:64
	global_load_dwordx4 v[220:223], v[40:41], off offset:80
	global_load_dwordx4 v[224:227], v[42:43], off offset:64
	global_load_dwordx4 v[228:231], v[42:43], off offset:80
	global_load_dwordx4 v[232:235], v[44:45], off offset:64
	global_load_dwordx4 v[236:239], v[44:45], off offset:80
	global_load_dwordx4 v[240:243], v[46:47], off offset:64
	global_load_dwordx4 v[244:247], v[46:47], off offset:80
	s_waitcnt vmcnt(8)
; DI void prep_wprime(const Params& p) {
;     ...
;     float a = 0.f;
;     for (int c4 = 0; c4 < 32; ++c4) {
;       float4 v = wi[c4];
;       a += v.x * cw[(c4 * 4 + 0) * 256] + v.y * cw[(c4 * 4 + 1) * 256] + v.z * cw[(c4 * 4 + 2) * 256] + v.w * cw[(c4 * 4 + 3) * 256];
;     }
	v_fmac_f32_e32 v248, v4, v92
	v_fmac_f32_e32 v249, v12, v92
	v_fmac_f32_e32 v250, v20, v92
	v_fmac_f32_e32 v251, v28, v92
	v_fmac_f32_e32 v248, v5, v93
	v_fmac_f32_e32 v249, v13, v93
	v_fmac_f32_e32 v250, v21, v93
	v_fmac_f32_e32 v251, v29, v93
	v_fmac_f32_e32 v248, v6, v94
	v_fmac_f32_e32 v249, v14, v94
	v_fmac_f32_e32 v250, v22, v94
	v_fmac_f32_e32 v251, v30, v94
	v_fmac_f32_e32 v248, v7, v95
	v_fmac_f32_e32 v249, v15, v95
	v_fmac_f32_e32 v250, v23, v95
	v_fmac_f32_e32 v251, v31, v95
	v_fmac_f32_e32 v248, v8, v96
	v_fmac_f32_e32 v249, v16, v96
	v_fmac_f32_e32 v250, v24, v96
	v_fmac_f32_e32 v251, v32, v96
	v_fmac_f32_e32 v248, v9, v97
	v_fmac_f32_e32 v249, v17, v97
	v_fmac_f32_e32 v250, v25, v97
	v_fmac_f32_e32 v251, v33, v97
	v_fmac_f32_e32 v248, v10, v98
	v_fmac_f32_e32 v249, v18, v98
	v_fmac_f32_e32 v250, v26, v98
	v_fmac_f32_e32 v251, v34, v98
	v_fmac_f32_e32 v248, v11, v99
	v_fmac_f32_e32 v249, v19, v99
	v_fmac_f32_e32 v250, v27, v99
	v_fmac_f32_e32 v251, v35, v99
	global_load_dwordx4 v[4:7], v[40:41], off offset:96
	global_load_dwordx4 v[8:11], v[40:41], off offset:112
	global_load_dwordx4 v[12:15], v[42:43], off offset:96
	global_load_dwordx4 v[16:19], v[42:43], off offset:112
	global_load_dwordx4 v[20:23], v[44:45], off offset:96
	global_load_dwordx4 v[24:27], v[44:45], off offset:112
	global_load_dwordx4 v[28:31], v[46:47], off offset:96
	global_load_dwordx4 v[32:35], v[46:47], off offset:112
	s_waitcnt vmcnt(8)
	v_fmac_f32_e32 v248, v216, v100
	v_fmac_f32_e32 v249, v224, v100
	v_fmac_f32_e32 v250, v232, v100
	v_fmac_f32_e32 v251, v240, v100
	v_fmac_f32_e32 v248, v217, v101
	v_fmac_f32_e32 v249, v225, v101
	v_fmac_f32_e32 v250, v233, v101
	v_fmac_f32_e32 v251, v241, v101
	v_fmac_f32_e32 v248, v218, v102
	v_fmac_f32_e32 v249, v226, v102
	v_fmac_f32_e32 v250, v234, v102
	v_fmac_f32_e32 v251, v242, v102
	v_fmac_f32_e32 v248, v219, v103
	v_fmac_f32_e32 v249, v227, v103
	v_fmac_f32_e32 v250, v235, v103
	v_fmac_f32_e32 v251, v243, v103
	v_fmac_f32_e32 v248, v220, v104
	v_fmac_f32_e32 v249, v228, v104
	v_fmac_f32_e32 v250, v236, v104
	v_fmac_f32_e32 v251, v244, v104
	v_fmac_f32_e32 v248, v221, v105
	v_fmac_f32_e32 v249, v229, v105
	v_fmac_f32_e32 v250, v237, v105
	v_fmac_f32_e32 v251, v245, v105
	v_fmac_f32_e32 v248, v222, v106
	v_fmac_f32_e32 v249, v230, v106
	v_fmac_f32_e32 v250, v238, v106
	v_fmac_f32_e32 v251, v246, v106
	v_fmac_f32_e32 v248, v223, v107
	v_fmac_f32_e32 v249, v231, v107
	v_fmac_f32_e32 v250, v239, v107
	v_fmac_f32_e32 v251, v247, v107
	global_load_dwordx4 v[216:219], v[40:41], off offset:128
	global_load_dwordx4 v[220:223], v[40:41], off offset:144
	global_load_dwordx4 v[224:227], v[42:43], off offset:128
	global_load_dwordx4 v[228:231], v[42:43], off offset:144
	global_load_dwordx4 v[232:235], v[44:45], off offset:128
	global_load_dwordx4 v[236:239], v[44:45], off offset:144
	global_load_dwordx4 v[240:243], v[46:47], off offset:128
	global_load_dwordx4 v[244:247], v[46:47], off offset:144
	s_waitcnt vmcnt(8)
	v_fmac_f32_e32 v248, v4, v108
	v_fmac_f32_e32 v249, v12, v108
	v_fmac_f32_e32 v250, v20, v108
	v_fmac_f32_e32 v251, v28, v108
	v_fmac_f32_e32 v248, v5, v109
	v_fmac_f32_e32 v249, v13, v109
	v_fmac_f32_e32 v250, v21, v109
	v_fmac_f32_e32 v251, v29, v109
	v_fmac_f32_e32 v248, v6, v110
	v_fmac_f32_e32 v249, v14, v110
	v_fmac_f32_e32 v250, v22, v110
	v_fmac_f32_e32 v251, v30, v110
	v_fmac_f32_e32 v248, v7, v111
	v_fmac_f32_e32 v249, v15, v111
	v_fmac_f32_e32 v250, v23, v111
	v_fmac_f32_e32 v251, v31, v111
	v_fmac_f32_e32 v248, v8, v112
	v_fmac_f32_e32 v249, v16, v112
	v_fmac_f32_e32 v250, v24, v112
	v_fmac_f32_e32 v251, v32, v112
	v_fmac_f32_e32 v248, v9, v113
	v_fmac_f32_e32 v249, v17, v113
	v_fmac_f32_e32 v250, v25, v113
	v_fmac_f32_e32 v251, v33, v113
	v_fmac_f32_e32 v248, v10, v114
	v_fmac_f32_e32 v249, v18, v114
	v_fmac_f32_e32 v250, v26, v114
	v_fmac_f32_e32 v251, v34, v114
	v_fmac_f32_e32 v248, v11, v115
	v_fmac_f32_e32 v249, v19, v115
	v_fmac_f32_e32 v250, v27, v115
	v_fmac_f32_e32 v251, v35, v115
	global_load_dwordx4 v[4:7], v[40:41], off offset:160
	global_load_dwordx4 v[8:11], v[40:41], off offset:176
	global_load_dwordx4 v[12:15], v[42:43], off offset:160
	global_load_dwordx4 v[16:19], v[42:43], off offset:176
	global_load_dwordx4 v[20:23], v[44:45], off offset:160
	global_load_dwordx4 v[24:27], v[44:45], off offset:176
	global_load_dwordx4 v[28:31], v[46:47], off offset:160
	global_load_dwordx4 v[32:35], v[46:47], off offset:176
	s_waitcnt vmcnt(8)
	v_fmac_f32_e32 v248, v216, v116
	v_fmac_f32_e32 v249, v224, v116
	v_fmac_f32_e32 v250, v232, v116
	v_fmac_f32_e32 v251, v240, v116
	v_fmac_f32_e32 v248, v217, v117
	v_fmac_f32_e32 v249, v225, v117
	v_fmac_f32_e32 v250, v233, v117
	v_fmac_f32_e32 v251, v241, v117
	v_fmac_f32_e32 v248, v218, v118
	v_fmac_f32_e32 v249, v226, v118
	v_fmac_f32_e32 v250, v234, v118
	v_fmac_f32_e32 v251, v242, v118
	v_fmac_f32_e32 v248, v219, v119
	v_fmac_f32_e32 v249, v227, v119
	v_fmac_f32_e32 v250, v235, v119
	v_fmac_f32_e32 v251, v243, v119
	v_fmac_f32_e32 v248, v220, v120
	v_fmac_f32_e32 v249, v228, v120
	v_fmac_f32_e32 v250, v236, v120
	v_fmac_f32_e32 v251, v244, v120
	v_fmac_f32_e32 v248, v221, v121
	v_fmac_f32_e32 v249, v229, v121
	v_fmac_f32_e32 v250, v237, v121
	v_fmac_f32_e32 v251, v245, v121
	v_fmac_f32_e32 v248, v222, v122
	v_fmac_f32_e32 v249, v230, v122
	v_fmac_f32_e32 v250, v238, v122
	v_fmac_f32_e32 v251, v246, v122
	v_fmac_f32_e32 v248, v223, v123
	v_fmac_f32_e32 v249, v231, v123
	v_fmac_f32_e32 v250, v239, v123
	v_fmac_f32_e32 v251, v247, v123
	global_load_dwordx4 v[216:219], v[40:41], off offset:192
	global_load_dwordx4 v[220:223], v[40:41], off offset:208
	global_load_dwordx4 v[224:227], v[42:43], off offset:192
	global_load_dwordx4 v[228:231], v[42:43], off offset:208
	global_load_dwordx4 v[232:235], v[44:45], off offset:192
	global_load_dwordx4 v[236:239], v[44:45], off offset:208
	global_load_dwordx4 v[240:243], v[46:47], off offset:192
	global_load_dwordx4 v[244:247], v[46:47], off offset:208
	s_waitcnt vmcnt(8)
; DI void prep_wprime(const Params& p) {
;     ...
;     float a = 0.f;
;     for (int c4 = 0; c4 < 32; ++c4) {
;       float4 v = wi[c4];
;       a += v.x * cw[(c4 * 4 + 0) * 256] + v.y * cw[(c4 * 4 + 1) * 256] + v.z * cw[(c4 * 4 + 2) * 256] + v.w * cw[(c4 * 4 + 3) * 256];
;     }
	v_fmac_f32_e32 v248, v4, v124
	v_fmac_f32_e32 v249, v12, v124
	v_fmac_f32_e32 v250, v20, v124
	v_fmac_f32_e32 v251, v28, v124
	v_fmac_f32_e32 v248, v5, v125
	v_fmac_f32_e32 v249, v13, v125
	v_fmac_f32_e32 v250, v21, v125
	v_fmac_f32_e32 v251, v29, v125
	v_fmac_f32_e32 v248, v6, v126
	v_fmac_f32_e32 v249, v14, v126
	v_fmac_f32_e32 v250, v22, v126
	v_fmac_f32_e32 v251, v30, v126
	v_fmac_f32_e32 v248, v7, v127
	v_fmac_f32_e32 v249, v15, v127
	v_fmac_f32_e32 v250, v23, v127
	v_fmac_f32_e32 v251, v31, v127
	v_fmac_f32_e32 v248, v8, v128
	v_fmac_f32_e32 v249, v16, v128
	v_fmac_f32_e32 v250, v24, v128
	v_fmac_f32_e32 v251, v32, v128
	v_fmac_f32_e32 v248, v9, v129
	v_fmac_f32_e32 v249, v17, v129
	v_fmac_f32_e32 v250, v25, v129
	v_fmac_f32_e32 v251, v33, v129
	v_fmac_f32_e32 v248, v10, v130
	v_fmac_f32_e32 v249, v18, v130
	v_fmac_f32_e32 v250, v26, v130
	v_fmac_f32_e32 v251, v34, v130
	v_fmac_f32_e32 v248, v11, v131
	v_fmac_f32_e32 v249, v19, v131
	v_fmac_f32_e32 v250, v27, v131
	v_fmac_f32_e32 v251, v35, v131
	global_load_dwordx4 v[4:7], v[40:41], off offset:224
	global_load_dwordx4 v[8:11], v[40:41], off offset:240
	global_load_dwordx4 v[12:15], v[42:43], off offset:224
	global_load_dwordx4 v[16:19], v[42:43], off offset:240
	global_load_dwordx4 v[20:23], v[44:45], off offset:224
	global_load_dwordx4 v[24:27], v[44:45], off offset:240
	global_load_dwordx4 v[28:31], v[46:47], off offset:224
	global_load_dwordx4 v[32:35], v[46:47], off offset:240
	s_waitcnt vmcnt(8)
	v_fmac_f32_e32 v248, v216, v132
	v_fmac_f32_e32 v249, v224, v132
	v_fmac_f32_e32 v250, v232, v132
	v_fmac_f32_e32 v251, v240, v132
	v_fmac_f32_e32 v248, v217, v133
	v_fmac_f32_e32 v249, v225, v133
	v_fmac_f32_e32 v250, v233, v133
	v_fmac_f32_e32 v251, v241, v133
	v_fmac_f32_e32 v248, v218, v134
	v_fmac_f32_e32 v249, v226, v134
	v_fmac_f32_e32 v250, v234, v134
	v_fmac_f32_e32 v251, v242, v134
	v_fmac_f32_e32 v248, v219, v135
	v_fmac_f32_e32 v249, v227, v135
	v_fmac_f32_e32 v250, v235, v135
	v_fmac_f32_e32 v251, v243, v135
	v_fmac_f32_e32 v248, v220, v136
	v_fmac_f32_e32 v249, v228, v136
	v_fmac_f32_e32 v250, v236, v136
	v_fmac_f32_e32 v251, v244, v136
	v_fmac_f32_e32 v248, v221, v137
	v_fmac_f32_e32 v249, v229, v137
	v_fmac_f32_e32 v250, v237, v137
	v_fmac_f32_e32 v251, v245, v137
	v_fmac_f32_e32 v248, v222, v138
	v_fmac_f32_e32 v249, v230, v138
	v_fmac_f32_e32 v250, v238, v138
	v_fmac_f32_e32 v251, v246, v138
	v_fmac_f32_e32 v248, v223, v139
	v_fmac_f32_e32 v249, v231, v139
	v_fmac_f32_e32 v250, v239, v139
	v_fmac_f32_e32 v251, v247, v139
	global_load_dwordx4 v[216:219], v[40:41], off offset:256
	global_load_dwordx4 v[220:223], v[40:41], off offset:272
	global_load_dwordx4 v[224:227], v[42:43], off offset:256
	global_load_dwordx4 v[228:231], v[42:43], off offset:272
	global_load_dwordx4 v[232:235], v[44:45], off offset:256
	global_load_dwordx4 v[236:239], v[44:45], off offset:272
	global_load_dwordx4 v[240:243], v[46:47], off offset:256
	global_load_dwordx4 v[244:247], v[46:47], off offset:272
	s_waitcnt vmcnt(8)
	v_fmac_f32_e32 v248, v4, v140
	v_fmac_f32_e32 v249, v12, v140
	v_fmac_f32_e32 v250, v20, v140
	v_fmac_f32_e32 v251, v28, v140
	v_fmac_f32_e32 v248, v5, v141
	v_fmac_f32_e32 v249, v13, v141
	v_fmac_f32_e32 v250, v21, v141
	v_fmac_f32_e32 v251, v29, v141
	v_fmac_f32_e32 v248, v6, v142
	v_fmac_f32_e32 v249, v14, v142
	v_fmac_f32_e32 v250, v22, v142
	v_fmac_f32_e32 v251, v30, v142
	v_fmac_f32_e32 v248, v7, v143
	v_fmac_f32_e32 v249, v15, v143
	v_fmac_f32_e32 v250, v23, v143
	v_fmac_f32_e32 v251, v31, v143
	v_fmac_f32_e32 v248, v8, v144
	v_fmac_f32_e32 v249, v16, v144
	v_fmac_f32_e32 v250, v24, v144
	v_fmac_f32_e32 v251, v32, v144
	v_fmac_f32_e32 v248, v9, v145
	v_fmac_f32_e32 v249, v17, v145
	v_fmac_f32_e32 v250, v25, v145
	v_fmac_f32_e32 v251, v33, v145
	v_fmac_f32_e32 v248, v10, v146
	v_fmac_f32_e32 v249, v18, v146
	v_fmac_f32_e32 v250, v26, v146
	v_fmac_f32_e32 v251, v34, v146
	v_fmac_f32_e32 v248, v11, v147
	v_fmac_f32_e32 v249, v19, v147
	v_fmac_f32_e32 v250, v27, v147
	v_fmac_f32_e32 v251, v35, v147
	global_load_dwordx4 v[4:7], v[40:41], off offset:288
	global_load_dwordx4 v[8:11], v[40:41], off offset:304
	global_load_dwordx4 v[12:15], v[42:43], off offset:288
	global_load_dwordx4 v[16:19], v[42:43], off offset:304
	global_load_dwordx4 v[20:23], v[44:45], off offset:288
	global_load_dwordx4 v[24:27], v[44:45], off offset:304
	global_load_dwordx4 v[28:31], v[46:47], off offset:288
	global_load_dwordx4 v[32:35], v[46:47], off offset:304
	s_waitcnt vmcnt(8)
	v_fmac_f32_e32 v248, v216, v148
	v_fmac_f32_e32 v249, v224, v148
	v_fmac_f32_e32 v250, v232, v148
	v_fmac_f32_e32 v251, v240, v148
	v_fmac_f32_e32 v248, v217, v149
	v_fmac_f32_e32 v249, v225, v149
	v_fmac_f32_e32 v250, v233, v149
	v_fmac_f32_e32 v251, v241, v149
	v_fmac_f32_e32 v248, v218, v150
	v_fmac_f32_e32 v249, v226, v150
	v_fmac_f32_e32 v250, v234, v150
	v_fmac_f32_e32 v251, v242, v150
	v_fmac_f32_e32 v248, v219, v151
	v_fmac_f32_e32 v249, v227, v151
	v_fmac_f32_e32 v250, v235, v151
	v_fmac_f32_e32 v251, v243, v151
	v_fmac_f32_e32 v248, v220, v152
	v_fmac_f32_e32 v249, v228, v152
	v_fmac_f32_e32 v250, v236, v152
	v_fmac_f32_e32 v251, v244, v152
	v_fmac_f32_e32 v248, v221, v153
	v_fmac_f32_e32 v249, v229, v153
	v_fmac_f32_e32 v250, v237, v153
	v_fmac_f32_e32 v251, v245, v153
	v_fmac_f32_e32 v248, v222, v154
	v_fmac_f32_e32 v249, v230, v154
	v_fmac_f32_e32 v250, v238, v154
	v_fmac_f32_e32 v251, v246, v154
	v_fmac_f32_e32 v248, v223, v155
	v_fmac_f32_e32 v249, v231, v155
	v_fmac_f32_e32 v250, v239, v155
	v_fmac_f32_e32 v251, v247, v155
	global_load_dwordx4 v[216:219], v[40:41], off offset:320
	global_load_dwordx4 v[220:223], v[40:41], off offset:336
	global_load_dwordx4 v[224:227], v[42:43], off offset:320
	global_load_dwordx4 v[228:231], v[42:43], off offset:336
	global_load_dwordx4 v[232:235], v[44:45], off offset:320
	global_load_dwordx4 v[236:239], v[44:45], off offset:336
	global_load_dwordx4 v[240:243], v[46:47], off offset:320
	global_load_dwordx4 v[244:247], v[46:47], off offset:336
	s_waitcnt vmcnt(8)
; DI void prep_wprime(const Params& p) {
;     ...
;     float a = 0.f;
;     for (int c4 = 0; c4 < 32; ++c4) {
;       float4 v = wi[c4];
;       a += v.x * cw[(c4 * 4 + 0) * 256] + v.y * cw[(c4 * 4 + 1) * 256] + v.z * cw[(c4 * 4 + 2) * 256] + v.w * cw[(c4 * 4 + 3) * 256];
;     }
	v_fmac_f32_e32 v248, v4, v156
	v_fmac_f32_e32 v249, v12, v156
	v_fmac_f32_e32 v250, v20, v156
	v_fmac_f32_e32 v251, v28, v156
	v_fmac_f32_e32 v248, v5, v157
	v_fmac_f32_e32 v249, v13, v157
	v_fmac_f32_e32 v250, v21, v157
	v_fmac_f32_e32 v251, v29, v157
	v_fmac_f32_e32 v248, v6, v158
	v_fmac_f32_e32 v249, v14, v158
	v_fmac_f32_e32 v250, v22, v158
	v_fmac_f32_e32 v251, v30, v158
	v_fmac_f32_e32 v248, v7, v159
	v_fmac_f32_e32 v249, v15, v159
	v_fmac_f32_e32 v250, v23, v159
	v_fmac_f32_e32 v251, v31, v159
	v_fmac_f32_e32 v248, v8, v160
	v_fmac_f32_e32 v249, v16, v160
	v_fmac_f32_e32 v250, v24, v160
	v_fmac_f32_e32 v251, v32, v160
	v_fmac_f32_e32 v248, v9, v161
	v_fmac_f32_e32 v249, v17, v161
	v_fmac_f32_e32 v250, v25, v161
	v_fmac_f32_e32 v251, v33, v161
	v_fmac_f32_e32 v248, v10, v162
	v_fmac_f32_e32 v249, v18, v162
	v_fmac_f32_e32 v250, v26, v162
	v_fmac_f32_e32 v251, v34, v162
	v_fmac_f32_e32 v248, v11, v163
	v_fmac_f32_e32 v249, v19, v163
	v_fmac_f32_e32 v250, v27, v163
	v_fmac_f32_e32 v251, v35, v163
	global_load_dwordx4 v[4:7], v[40:41], off offset:352
	global_load_dwordx4 v[8:11], v[40:41], off offset:368
	global_load_dwordx4 v[12:15], v[42:43], off offset:352
	global_load_dwordx4 v[16:19], v[42:43], off offset:368
	global_load_dwordx4 v[20:23], v[44:45], off offset:352
	global_load_dwordx4 v[24:27], v[44:45], off offset:368
	global_load_dwordx4 v[28:31], v[46:47], off offset:352
	global_load_dwordx4 v[32:35], v[46:47], off offset:368
	s_waitcnt vmcnt(8)
	v_fmac_f32_e32 v248, v216, v164
	v_fmac_f32_e32 v249, v224, v164
	v_fmac_f32_e32 v250, v232, v164
	v_fmac_f32_e32 v251, v240, v164
	v_fmac_f32_e32 v248, v217, v165
	v_fmac_f32_e32 v249, v225, v165
	v_fmac_f32_e32 v250, v233, v165
	v_fmac_f32_e32 v251, v241, v165
	v_fmac_f32_e32 v248, v218, v166
	v_fmac_f32_e32 v249, v226, v166
	v_fmac_f32_e32 v250, v234, v166
	v_fmac_f32_e32 v251, v242, v166
	v_fmac_f32_e32 v248, v219, v167
	v_fmac_f32_e32 v249, v227, v167
	v_fmac_f32_e32 v250, v235, v167
	v_fmac_f32_e32 v251, v243, v167
	v_fmac_f32_e32 v248, v220, v168
	v_fmac_f32_e32 v249, v228, v168
	v_fmac_f32_e32 v250, v236, v168
	v_fmac_f32_e32 v251, v244, v168
	v_fmac_f32_e32 v248, v221, v169
	v_fmac_f32_e32 v249, v229, v169
	v_fmac_f32_e32 v250, v237, v169
	v_fmac_f32_e32 v251, v245, v169
	v_fmac_f32_e32 v248, v222, v170
	v_fmac_f32_e32 v249, v230, v170
	v_fmac_f32_e32 v250, v238, v170
	v_fmac_f32_e32 v251, v246, v170
	v_fmac_f32_e32 v248, v223, v171
	v_fmac_f32_e32 v249, v231, v171
	v_fmac_f32_e32 v250, v239, v171
	v_fmac_f32_e32 v251, v247, v171
	global_load_dwordx4 v[216:219], v[40:41], off offset:384
	global_load_dwordx4 v[220:223], v[40:41], off offset:400
	global_load_dwordx4 v[224:227], v[42:43], off offset:384
	global_load_dwordx4 v[228:231], v[42:43], off offset:400
	global_load_dwordx4 v[232:235], v[44:45], off offset:384
	global_load_dwordx4 v[236:239], v[44:45], off offset:400
	global_load_dwordx4 v[240:243], v[46:47], off offset:384
	global_load_dwordx4 v[244:247], v[46:47], off offset:400
	s_waitcnt vmcnt(8)
	v_fmac_f32_e32 v248, v4, v172
	v_fmac_f32_e32 v249, v12, v172
	v_fmac_f32_e32 v250, v20, v172
	v_fmac_f32_e32 v251, v28, v172
	v_fmac_f32_e32 v248, v5, v173
	v_fmac_f32_e32 v249, v13, v173
	v_fmac_f32_e32 v250, v21, v173
	v_fmac_f32_e32 v251, v29, v173
	v_fmac_f32_e32 v248, v6, v174
	v_fmac_f32_e32 v249, v14, v174
	v_fmac_f32_e32 v250, v22, v174
	v_fmac_f32_e32 v251, v30, v174
	v_fmac_f32_e32 v248, v7, v175
	v_fmac_f32_e32 v249, v15, v175
	v_fmac_f32_e32 v250, v23, v175
	v_fmac_f32_e32 v251, v31, v175
	v_fmac_f32_e32 v248, v8, v176
	v_fmac_f32_e32 v249, v16, v176
	v_fmac_f32_e32 v250, v24, v176
	v_fmac_f32_e32 v251, v32, v176
	v_fmac_f32_e32 v248, v9, v177
	v_fmac_f32_e32 v249, v17, v177
	v_fmac_f32_e32 v250, v25, v177
	v_fmac_f32_e32 v251, v33, v177
	v_fmac_f32_e32 v248, v10, v178
	v_fmac_f32_e32 v249, v18, v178
	v_fmac_f32_e32 v250, v26, v178
	v_fmac_f32_e32 v251, v34, v178
	v_fmac_f32_e32 v248, v11, v179
	v_fmac_f32_e32 v249, v19, v179
	v_fmac_f32_e32 v250, v27, v179
	v_fmac_f32_e32 v251, v35, v179
	global_load_dwordx4 v[4:7], v[40:41], off offset:416
	global_load_dwordx4 v[8:11], v[40:41], off offset:432
	global_load_dwordx4 v[12:15], v[42:43], off offset:416
	global_load_dwordx4 v[16:19], v[42:43], off offset:432
	global_load_dwordx4 v[20:23], v[44:45], off offset:416
	global_load_dwordx4 v[24:27], v[44:45], off offset:432
	global_load_dwordx4 v[28:31], v[46:47], off offset:416
	global_load_dwordx4 v[32:35], v[46:47], off offset:432
	s_waitcnt vmcnt(8)
; DI u16 f2bf(float x) { return (u16)(pack2(x, 0.f) & 0xffffu); }
; DI void prep_wprime(const Params& p) {
;     ...
;   for (long id = gt; id < 2048L * 1024; id += gn) {
;     const int k = (int)(id & 1023), np = (int)(id >> 10), g = np >> 8, col = np & 255;
;     const float4* wi = (const float4*)(p.fn_w_in + (long)k * 2048 + g * 128);
;     const float* cw = p.CW + (long)g * 128 * 256 + col;
;     float a = 0.f;
;     for (int c4 = 0; c4 < 32; ++c4) {
;       float4 v = wi[c4];
;       a += v.x * cw[(c4 * 4 + 0) * 256] + v.y * cw[(c4 * 4 + 1) * 256] + v.z * cw[(c4 * 4 + 2) * 256] + v.w * cw[(c4 * 4 + 3) * 256];
;     }
;     p.Wfn[id] = f2bf(a * p.norm_g[k]);
;   }
	v_fmac_f32_e32 v248, v216, v184
	v_fmac_f32_e32 v249, v224, v184
	v_fmac_f32_e32 v250, v232, v184
	v_fmac_f32_e32 v251, v240, v184
	v_fmac_f32_e32 v248, v217, v185
	v_fmac_f32_e32 v249, v225, v185
	v_fmac_f32_e32 v250, v233, v185
	v_fmac_f32_e32 v251, v241, v185
	v_fmac_f32_e32 v248, v218, v186
	v_fmac_f32_e32 v249, v226, v186
	v_fmac_f32_e32 v250, v234, v186
	v_fmac_f32_e32 v251, v242, v186
	v_fmac_f32_e32 v248, v219, v187
	v_fmac_f32_e32 v249, v227, v187
	v_fmac_f32_e32 v250, v235, v187
	v_fmac_f32_e32 v251, v243, v187
	v_fmac_f32_e32 v248, v220, v188
	v_fmac_f32_e32 v249, v228, v188
	v_fmac_f32_e32 v250, v236, v188
	v_fmac_f32_e32 v251, v244, v188
	v_fmac_f32_e32 v248, v221, v189
	v_fmac_f32_e32 v249, v229, v189
	v_fmac_f32_e32 v250, v237, v189
	v_fmac_f32_e32 v251, v245, v189
	v_fmac_f32_e32 v248, v222, v190
	v_fmac_f32_e32 v249, v230, v190
	v_fmac_f32_e32 v250, v238, v190
	v_fmac_f32_e32 v251, v246, v190
	v_fmac_f32_e32 v248, v223, v191
	v_fmac_f32_e32 v249, v231, v191
	v_fmac_f32_e32 v250, v239, v191
	v_fmac_f32_e32 v251, v247, v191
	global_load_dwordx4 v[216:219], v[40:41], off offset:448
	global_load_dwordx4 v[220:223], v[40:41], off offset:464
	global_load_dwordx4 v[224:227], v[42:43], off offset:448
	global_load_dwordx4 v[228:231], v[42:43], off offset:464
	global_load_dwordx4 v[232:235], v[44:45], off offset:448
	global_load_dwordx4 v[236:239], v[44:45], off offset:464
	global_load_dwordx4 v[240:243], v[46:47], off offset:448
	global_load_dwordx4 v[244:247], v[46:47], off offset:464
	s_waitcnt vmcnt(8)
	v_fmac_f32_e32 v248, v4, v192
	v_fmac_f32_e32 v249, v12, v192
	v_fmac_f32_e32 v250, v20, v192
	v_fmac_f32_e32 v251, v28, v192
	v_fmac_f32_e32 v248, v5, v193
	v_fmac_f32_e32 v249, v13, v193
	v_fmac_f32_e32 v250, v21, v193
	v_fmac_f32_e32 v251, v29, v193
	v_fmac_f32_e32 v248, v6, v194
	v_fmac_f32_e32 v249, v14, v194
	v_fmac_f32_e32 v250, v22, v194
	v_fmac_f32_e32 v251, v30, v194
	v_fmac_f32_e32 v248, v7, v195
	v_fmac_f32_e32 v249, v15, v195
	v_fmac_f32_e32 v250, v23, v195
	v_fmac_f32_e32 v251, v31, v195
	v_fmac_f32_e32 v248, v8, v196
	v_fmac_f32_e32 v249, v16, v196
	v_fmac_f32_e32 v250, v24, v196
	v_fmac_f32_e32 v251, v32, v196
	v_fmac_f32_e32 v248, v9, v197
	v_fmac_f32_e32 v249, v17, v197
	v_fmac_f32_e32 v250, v25, v197
	v_fmac_f32_e32 v251, v33, v197
	v_fmac_f32_e32 v248, v10, v198
	v_fmac_f32_e32 v249, v18, v198
	v_fmac_f32_e32 v250, v26, v198
	v_fmac_f32_e32 v251, v34, v198
	v_fmac_f32_e32 v248, v11, v199
	v_fmac_f32_e32 v249, v19, v199
	v_fmac_f32_e32 v250, v27, v199
	v_fmac_f32_e32 v251, v35, v199
	global_load_dwordx4 v[4:7], v[40:41], off offset:480
	global_load_dwordx4 v[8:11], v[40:41], off offset:496
	global_load_dwordx4 v[12:15], v[42:43], off offset:480
	global_load_dwordx4 v[16:19], v[42:43], off offset:496
	global_load_dwordx4 v[20:23], v[44:45], off offset:480
	global_load_dwordx4 v[24:27], v[44:45], off offset:496
	global_load_dwordx4 v[28:31], v[46:47], off offset:480
	global_load_dwordx4 v[32:35], v[46:47], off offset:496
	s_waitcnt vmcnt(8)
	v_fmac_f32_e32 v248, v216, v200
	v_fmac_f32_e32 v249, v224, v200
	v_fmac_f32_e32 v250, v232, v200
	v_fmac_f32_e32 v251, v240, v200
	v_fmac_f32_e32 v248, v217, v201
	v_fmac_f32_e32 v249, v225, v201
	v_fmac_f32_e32 v250, v233, v201
	v_fmac_f32_e32 v251, v241, v201
	v_fmac_f32_e32 v248, v218, v202
	v_fmac_f32_e32 v249, v226, v202
	v_fmac_f32_e32 v250, v234, v202
	v_fmac_f32_e32 v251, v242, v202
	v_fmac_f32_e32 v248, v219, v203
	v_fmac_f32_e32 v249, v227, v203
	v_fmac_f32_e32 v250, v235, v203
	v_fmac_f32_e32 v251, v243, v203
	v_fmac_f32_e32 v248, v220, v204
	v_fmac_f32_e32 v249, v228, v204
	v_fmac_f32_e32 v250, v236, v204
	v_fmac_f32_e32 v251, v244, v204
	v_fmac_f32_e32 v248, v221, v205
	v_fmac_f32_e32 v249, v229, v205
	v_fmac_f32_e32 v250, v237, v205
	v_fmac_f32_e32 v251, v245, v205
	v_fmac_f32_e32 v248, v222, v206
	v_fmac_f32_e32 v249, v230, v206
	v_fmac_f32_e32 v250, v238, v206
	v_fmac_f32_e32 v251, v246, v206
	v_fmac_f32_e32 v248, v223, v207
	v_fmac_f32_e32 v249, v231, v207
	v_fmac_f32_e32 v250, v239, v207
	v_fmac_f32_e32 v251, v247, v207
	s_waitcnt vmcnt(0)
	v_fmac_f32_e32 v248, v4, v208
	v_fmac_f32_e32 v249, v12, v208
	v_fmac_f32_e32 v250, v20, v208
	v_fmac_f32_e32 v251, v28, v208
	v_fmac_f32_e32 v248, v5, v209
	v_fmac_f32_e32 v249, v13, v209
	v_fmac_f32_e32 v250, v21, v209
	v_fmac_f32_e32 v251, v29, v209
	v_fmac_f32_e32 v248, v6, v210
	v_fmac_f32_e32 v249, v14, v210
	v_fmac_f32_e32 v250, v22, v210
	v_fmac_f32_e32 v251, v30, v210
	v_fmac_f32_e32 v248, v7, v211
	v_fmac_f32_e32 v249, v15, v211
	v_fmac_f32_e32 v250, v23, v211
	v_fmac_f32_e32 v251, v31, v211
	v_fmac_f32_e32 v248, v8, v212
	v_fmac_f32_e32 v249, v16, v212
	v_fmac_f32_e32 v250, v24, v212
	v_fmac_f32_e32 v251, v32, v212
	v_fmac_f32_e32 v248, v9, v213
	v_fmac_f32_e32 v249, v17, v213
	v_fmac_f32_e32 v250, v25, v213
	v_fmac_f32_e32 v251, v33, v213
	v_fmac_f32_e32 v248, v10, v214
	v_fmac_f32_e32 v249, v18, v214
	v_fmac_f32_e32 v250, v26, v214
	v_fmac_f32_e32 v251, v34, v214
	v_fmac_f32_e32 v248, v11, v215
	v_fmac_f32_e32 v249, v19, v215
	v_fmac_f32_e32 v250, v27, v215
	v_fmac_f32_e32 v251, v35, v215
	v_mul_f32_e32 v248, v248, v52
	v_mul_f32_e32 v249, v249, v53
	v_mul_f32_e32 v250, v250, v54
	v_mul_f32_e32 v251, v251, v55
	v_cvt_pk_bf16_f32 v56, v248, v249
	v_cvt_pk_bf16_f32 v57, v250, v251
	global_store_dwordx2 v[48:49], v[56:57], off
	s_add_i32 s8, s8, s9
	s_cmp_lt_u32 s8, 0x2000
	s_cbranch_scc1 .Lwp_tile
.Lwp_done:
.LBB0_67:
	s_or_b64 exec, exec, s[6:7]
	s_barrier
	s_and_saveexec_b64 s[6:7], s[2:3]
	s_cbranch_execz .LBB0_77
	buffer_wbl2 sc1
	s_waitcnt vmcnt(0)
	s_load_dwordx2 s[8:9], s[96:97], 0x58
	v_mov_b32_e32 v2, 0
	s_mov_b64 s[10:11], exec
	v_mbcnt_lo_u32_b32 v1, s10, 0
	v_mbcnt_hi_u32_b32 v1, s11, v1
	s_waitcnt lgkmcnt(0)
	global_load_dword v0, v2, s[8:9] offset:40
	v_cmp_eq_u32_e32 vcc, 0, v1
	s_and_saveexec_b64 s[12:13], vcc
	s_cbranch_execz .LBB0_70
	s_bcnt1_i32_b64 s10, s[10:11]
	v_mov_b32_e32 v3, s10
	global_atomic_add v3, v2, v3, s[8:9] offset:32 sc0
